# dequeue fast path no longer waits for the wave's outstanding stores when the ticket was prefetched
# speedup vs baseline: 1.0113x; 1.0028x over previous
.Ldq_have:
	v_mov_b32_e32 v3, v250
	s_mov_b32 s99, 0
	s_or_b64 exec, exec, s[4:5]
	s_branch .Ldq_nowait

.Ldq_nowait:
	v_readfirstlane_b32 s4, v3
	v_mov_b32_e32 v3, s3
	s_nop 0
	v_add_u32_e32 v2, s4, v2
	ds_write_b32 v3, v2
